# bundle3 + attention epilogue g_subln from LDS + in-proj K-loop first-iteration waits count draining epilogue stores
# speedup vs baseline: 1.0151x; 1.0041x over previous
.LBB0_156:
	s_cmp_gt_u32 s75, 1
	s_cselect_b32 s92, 1, 0
	s_ashr_i32 s15, s14, 31
	s_lshl_b64 s[18:19], s[14:15], 19
	s_add_u32 s18, s54, s18
	s_addc_u32 s19, s55, s19
	s_and_b64 s[20:21], s[16:17], exec
	s_cselect_b32 s15, s19, s27
	s_cselect_b32 s23, s18, s26
	s_ashr_i32 s13, s12, 31
	s_lshl_b64 s[20:21], s[12:13], 19
	s_add_u32 s20, s3, s20
	s_addc_u32 s21, s68, s21
	s_and_b64 s[30:31], s[16:17], exec
	s_cselect_b32 s13, s21, s29
	s_cselect_b32 s25, s20, s28
	s_add_u32 s26, s26, 0x40080
	s_addc_u32 s27, s27, 0
	s_add_u32 s36, s28, 0x100
	v_mov_b32_e32 v0, 0
	s_addc_u32 s37, s29, 0
	s_mov_b32 s38, -2
	v_mov_b32_e32 v1, v0
	v_mov_b32_e32 v2, v0
	v_mov_b32_e32 v3, v0
	v_mov_b32_e32 v4, v0
	v_mov_b32_e32 v5, v0
	v_mov_b32_e32 v6, v0
	v_mov_b32_e32 v7, v0
	v_mov_b32_e32 v16, v0
	v_mov_b32_e32 v17, v0
	v_mov_b32_e32 v18, v0
	v_mov_b32_e32 v19, v0
	v_mov_b32_e32 v20, v0
	v_mov_b32_e32 v21, v0
	v_mov_b32_e32 v22, v0
	v_mov_b32_e32 v23, v0
	v_mov_b32_e32 v32, v0
	v_mov_b32_e32 v33, v0
	v_mov_b32_e32 v34, v0
	v_mov_b32_e32 v35, v0
	v_mov_b32_e32 v36, v0
	v_mov_b32_e32 v37, v0
	v_mov_b32_e32 v38, v0
	v_mov_b32_e32 v39, v0
	v_mov_b32_e32 v48, v0
	v_mov_b32_e32 v49, v0
	v_mov_b32_e32 v50, v0
	v_mov_b32_e32 v51, v0
	v_mov_b32_e32 v52, v0
	v_mov_b32_e32 v53, v0
	v_mov_b32_e32 v54, v0
	v_mov_b32_e32 v55, v0
	v_mov_b32_e32 v8, v0
	v_mov_b32_e32 v9, v0
	v_mov_b32_e32 v10, v0
	v_mov_b32_e32 v11, v0
	v_mov_b32_e32 v12, v0
	v_mov_b32_e32 v13, v0
	v_mov_b32_e32 v14, v0
	v_mov_b32_e32 v15, v0
	v_mov_b32_e32 v24, v0
	v_mov_b32_e32 v25, v0
	v_mov_b32_e32 v26, v0
	v_mov_b32_e32 v27, v0
	v_mov_b32_e32 v28, v0
	v_mov_b32_e32 v29, v0
	v_mov_b32_e32 v30, v0
	v_mov_b32_e32 v31, v0
	v_mov_b32_e32 v40, v0
	v_mov_b32_e32 v41, v0
	v_mov_b32_e32 v42, v0
	v_mov_b32_e32 v43, v0
	v_mov_b32_e32 v44, v0
	v_mov_b32_e32 v45, v0
	v_mov_b32_e32 v46, v0
	v_mov_b32_e32 v47, v0
	v_mov_b32_e32 v56, v0
	v_mov_b32_e32 v57, v0
	v_mov_b32_e32 v58, v0
	v_mov_b32_e32 v59, v0
	v_mov_b32_e32 v60, v0
	v_mov_b32_e32 v61, v0
	v_mov_b32_e32 v62, v0
	v_mov_b32_e32 v63, v0
	v_mov_b32_e32 v64, v0
	v_mov_b32_e32 v65, v0
	v_mov_b32_e32 v66, v0
	v_mov_b32_e32 v67, v0
	v_mov_b32_e32 v68, v0
	v_mov_b32_e32 v69, v0
	v_mov_b32_e32 v70, v0
	v_mov_b32_e32 v71, v0
	v_mov_b32_e32 v80, v0
	v_mov_b32_e32 v81, v0
	v_mov_b32_e32 v82, v0
	v_mov_b32_e32 v83, v0
	v_mov_b32_e32 v84, v0
	v_mov_b32_e32 v85, v0
	v_mov_b32_e32 v86, v0
	v_mov_b32_e32 v87, v0
	v_mov_b32_e32 v96, v0
	v_mov_b32_e32 v97, v0
	v_mov_b32_e32 v98, v0
	v_mov_b32_e32 v99, v0
	v_mov_b32_e32 v100, v0
	v_mov_b32_e32 v101, v0
	v_mov_b32_e32 v102, v0
	v_mov_b32_e32 v103, v0
	v_mov_b32_e32 v112, v0
	v_mov_b32_e32 v113, v0
	v_mov_b32_e32 v114, v0
	v_mov_b32_e32 v115, v0
	v_mov_b32_e32 v116, v0
	v_mov_b32_e32 v117, v0
	v_mov_b32_e32 v118, v0
	v_mov_b32_e32 v119, v0
	v_mov_b32_e32 v72, v0
	v_mov_b32_e32 v73, v0
	v_mov_b32_e32 v74, v0
	v_mov_b32_e32 v75, v0
	v_mov_b32_e32 v76, v0
	v_mov_b32_e32 v77, v0
	v_mov_b32_e32 v78, v0
	v_mov_b32_e32 v79, v0
	v_mov_b32_e32 v88, v0
	v_mov_b32_e32 v89, v0
	v_mov_b32_e32 v90, v0
	v_mov_b32_e32 v91, v0
	v_mov_b32_e32 v92, v0
	v_mov_b32_e32 v93, v0
	v_mov_b32_e32 v94, v0
	v_mov_b32_e32 v95, v0
	v_mov_b32_e32 v104, v0
	v_mov_b32_e32 v105, v0
	v_mov_b32_e32 v106, v0
	v_mov_b32_e32 v107, v0
	v_mov_b32_e32 v108, v0
	v_mov_b32_e32 v109, v0
	v_mov_b32_e32 v110, v0
	v_mov_b32_e32 v111, v0
	v_mov_b32_e32 v120, v0
	v_mov_b32_e32 v121, v0
	v_mov_b32_e32 v122, v0
	v_mov_b32_e32 v123, v0
	v_mov_b32_e32 v124, v0
	v_mov_b32_e32 v125, v0
	v_mov_b32_e32 v126, v0
	v_mov_b32_e32 v127, v0
.LBB0_157:
	v_add_u32_e32 v172, s81, v175
	ds_read_b128 v[164:167], v172
	ds_read_b128 v[168:171], v172 offset:1024
	ds_read_b128 v[182:185], v172 offset:2048
	ds_read_b128 v[186:189], v172 offset:3072
	v_add_u32_e32 v172, s82, v175
	ds_read_b128 v[190:193], v172
	ds_read_b128 v[194:197], v172 offset:1024
	ds_read_b128 v[200:203], v172 offset:2048
	ds_read_b128 v[204:207], v172 offset:3072
	s_add_u32 s28, s26, 0xfffc0080
	s_addc_u32 s29, s27, -1
	s_cmp_eq_u32 s38, 12
	s_cselect_b32 s31, s15, s29
	s_cselect_b32 s30, s23, s28
	s_cselect_b32 s29, s13, s37
	s_cselect_b32 s28, s25, s36
	v_lshl_add_u64 v[172:173], s[26:27], 0, v[158:159]
	s_add_i32 m0, s71, 0xc000
	ds_read_b128 v[208:211], v180
	ds_read_b128 v[212:215], v180 offset:1024
	ds_read_b128 v[216:219], v180 offset:2048
	ds_read_b128 v[220:223], v180 offset:3072
	ds_read_b128 v[224:227], v180 offset:4096
	ds_read_b128 v[228:231], v180 offset:5120
	ds_read_b128 v[232:235], v180 offset:6144
	ds_read_b128 v[236:239], v180 offset:7168
	global_load_lds_dwordx4 v[172:173], off
	v_lshl_add_u64 v[172:173], s[26:27], 0, v[160:161]
	s_add_i32 m0, s71, 0xe000
	s_nop 0
	global_load_lds_dwordx4 v[172:173], off
	s_cmp_eq_u32 s92, 0
	s_cbranch_scc1 .Lp1_w8_0
	s_waitcnt vmcnt(24)
	s_branch .Lp1_wd_0
.Lp1_w8_0:
	s_waitcnt vmcnt(8)
.Lp1_wd_0:
	s_waitcnt lgkmcnt(0)
	s_barrier
	s_setprio 1
	s_waitcnt lgkmcnt(0)
	v_mfma_f32_16x16x32_bf16 v[124:127], v[164:167], v[208:211], v[124:127]
	v_mfma_f32_16x16x32_bf16 v[120:123], v[182:185], v[208:211], v[120:123]
	v_mfma_f32_16x16x32_bf16 v[108:111], v[164:167], v[216:219], v[108:111]
	v_mfma_f32_16x16x32_bf16 v[104:107], v[182:185], v[216:219], v[104:107]
	v_mfma_f32_16x16x32_bf16 v[92:95], v[164:167], v[224:227], v[92:95]
	v_mfma_f32_16x16x32_bf16 v[88:91], v[182:185], v[224:227], v[88:91]
	v_mfma_f32_16x16x32_bf16 v[76:79], v[164:167], v[232:235], v[76:79]
	v_mfma_f32_16x16x32_bf16 v[72:75], v[182:185], v[232:235], v[72:75]
	v_mfma_f32_16x16x32_bf16 v[124:127], v[168:171], v[212:215], v[124:127]
	v_mfma_f32_16x16x32_bf16 v[120:123], v[186:189], v[212:215], v[120:123]
	v_mfma_f32_16x16x32_bf16 v[108:111], v[168:171], v[220:223], v[108:111]
	v_mfma_f32_16x16x32_bf16 v[104:107], v[186:189], v[220:223], v[104:107]
	v_mfma_f32_16x16x32_bf16 v[92:95], v[168:171], v[228:231], v[92:95]
	v_mfma_f32_16x16x32_bf16 v[88:91], v[186:189], v[228:231], v[88:91]
	v_mfma_f32_16x16x32_bf16 v[76:79], v[168:171], v[236:239], v[76:79]
	v_mfma_f32_16x16x32_bf16 v[72:75], v[186:189], v[236:239], v[72:75]
	s_setprio 0
	s_setprio 1
	v_mfma_f32_16x16x32_bf16 v[116:119], v[190:193], v[208:211], v[116:119]
	v_mfma_f32_16x16x32_bf16 v[112:115], v[200:203], v[208:211], v[112:115]
	v_mfma_f32_16x16x32_bf16 v[100:103], v[190:193], v[216:219], v[100:103]
	v_mfma_f32_16x16x32_bf16 v[96:99], v[200:203], v[216:219], v[96:99]
	v_mfma_f32_16x16x32_bf16 v[84:87], v[190:193], v[224:227], v[84:87]
	v_mfma_f32_16x16x32_bf16 v[80:83], v[200:203], v[224:227], v[80:83]
	v_mfma_f32_16x16x32_bf16 v[68:71], v[190:193], v[232:235], v[68:71]
	v_mfma_f32_16x16x32_bf16 v[64:67], v[200:203], v[232:235], v[64:67]
	v_mfma_f32_16x16x32_bf16 v[116:119], v[194:197], v[212:215], v[116:119]
	v_mfma_f32_16x16x32_bf16 v[112:115], v[204:207], v[212:215], v[112:115]
	v_mfma_f32_16x16x32_bf16 v[100:103], v[194:197], v[220:223], v[100:103]
	v_mfma_f32_16x16x32_bf16 v[96:99], v[204:207], v[220:223], v[96:99]
	v_mfma_f32_16x16x32_bf16 v[84:87], v[194:197], v[228:231], v[84:87]
	v_mfma_f32_16x16x32_bf16 v[80:83], v[204:207], v[228:231], v[80:83]
	v_mfma_f32_16x16x32_bf16 v[68:71], v[194:197], v[236:239], v[68:71]
	v_mfma_f32_16x16x32_bf16 v[64:67], v[204:207], v[236:239], v[64:67]
	s_setprio 0
	s_barrier
	s_add_i32 s39, s81, s70
	v_lshl_add_u64 v[172:173], s[28:29], 0, v[130:131]
	s_mov_b32 m0, s39
	ds_read_b128 v[208:211], v180 offset:16384
	ds_read_b128 v[212:215], v180 offset:17408
	ds_read_b128 v[216:219], v180 offset:18432
	ds_read_b128 v[220:223], v180 offset:19456
	ds_read_b128 v[224:227], v180 offset:20480
	ds_read_b128 v[228:231], v180 offset:21504
	ds_read_b128 v[232:235], v180 offset:22528
	ds_read_b128 v[236:239], v180 offset:23552
	global_load_lds_dwordx4 v[172:173], off
	s_add_i32 m0, s39, 0x2000
	s_add_u32 s40, s28, 0x40000
	v_lshl_add_u64 v[240:241], s[28:29], 0, v[134:135]
	s_addc_u32 s41, s29, 0
	s_add_i32 s39, s82, s70
	global_load_lds_dwordx4 v[240:241], off
	v_lshl_add_u64 v[242:243], s[40:41], 0, v[130:131]
	s_mov_b32 m0, s39
	v_lshl_add_u64 v[244:245], s[30:31], 0, v[132:133]
	global_load_lds_dwordx4 v[242:243], off
	v_lshl_add_u64 v[242:243], s[40:41], 0, v[134:135]
	s_add_i32 m0, s39, 0x2000
	s_nop 0
	global_load_lds_dwordx4 v[242:243], off
	v_lshl_add_u64 v[242:243], s[30:31], 0, v[128:129]
	s_mov_b32 m0, s71
	s_nop 0
	global_load_lds_dwordx4 v[242:243], off
	s_mov_b32 m0, s72
	s_nop 0
	global_load_lds_dwordx4 v[244:245], off
	s_cmp_eq_u32 s92, 0
	s_cbranch_scc1 .Lp1_w8_1
	s_waitcnt vmcnt(24)
	s_branch .Lp1_wd_1

.Lp1_wd_1:
	s_mov_b32 s92, 0
	s_waitcnt lgkmcnt(0)
	s_barrier
	s_setprio 1
	s_waitcnt lgkmcnt(0)
	v_mfma_f32_16x16x32_bf16 v[60:63], v[164:167], v[208:211], v[60:63]
	v_mfma_f32_16x16x32_bf16 v[56:59], v[182:185], v[208:211], v[56:59]
	v_mfma_f32_16x16x32_bf16 v[44:47], v[164:167], v[216:219], v[44:47]
	v_mfma_f32_16x16x32_bf16 v[40:43], v[182:185], v[216:219], v[40:43]
	v_mfma_f32_16x16x32_bf16 v[28:31], v[164:167], v[224:227], v[28:31]
	v_mfma_f32_16x16x32_bf16 v[24:27], v[182:185], v[224:227], v[24:27]
	v_mfma_f32_16x16x32_bf16 v[12:15], v[164:167], v[232:235], v[12:15]
	v_mfma_f32_16x16x32_bf16 v[8:11], v[182:185], v[232:235], v[8:11]
	v_mfma_f32_16x16x32_bf16 v[60:63], v[168:171], v[212:215], v[60:63]
	v_mfma_f32_16x16x32_bf16 v[56:59], v[186:189], v[212:215], v[56:59]
	v_mfma_f32_16x16x32_bf16 v[44:47], v[168:171], v[220:223], v[44:47]
	v_mfma_f32_16x16x32_bf16 v[40:43], v[186:189], v[220:223], v[40:43]
	v_mfma_f32_16x16x32_bf16 v[28:31], v[168:171], v[228:231], v[28:31]
	v_mfma_f32_16x16x32_bf16 v[24:27], v[186:189], v[228:231], v[24:27]
	v_mfma_f32_16x16x32_bf16 v[12:15], v[168:171], v[236:239], v[12:15]
	v_mfma_f32_16x16x32_bf16 v[8:11], v[186:189], v[236:239], v[8:11]
	s_setprio 0
	s_setprio 1
	v_mfma_f32_16x16x32_bf16 v[52:55], v[190:193], v[208:211], v[52:55]
	v_mfma_f32_16x16x32_bf16 v[48:51], v[200:203], v[208:211], v[48:51]
	v_mfma_f32_16x16x32_bf16 v[36:39], v[190:193], v[216:219], v[36:39]
	v_mfma_f32_16x16x32_bf16 v[32:35], v[200:203], v[216:219], v[32:35]
	v_mfma_f32_16x16x32_bf16 v[20:23], v[190:193], v[224:227], v[20:23]
	v_mfma_f32_16x16x32_bf16 v[16:19], v[200:203], v[224:227], v[16:19]
	v_mfma_f32_16x16x32_bf16 v[4:7], v[190:193], v[232:235], v[4:7]
	v_mfma_f32_16x16x32_bf16 v[0:3], v[200:203], v[232:235], v[0:3]
	v_mfma_f32_16x16x32_bf16 v[52:55], v[194:197], v[212:215], v[52:55]
	v_mfma_f32_16x16x32_bf16 v[48:51], v[204:207], v[212:215], v[48:51]
	v_mfma_f32_16x16x32_bf16 v[36:39], v[194:197], v[220:223], v[36:39]
	v_mfma_f32_16x16x32_bf16 v[32:35], v[204:207], v[220:223], v[32:35]
	v_mfma_f32_16x16x32_bf16 v[20:23], v[194:197], v[228:231], v[20:23]
	v_mfma_f32_16x16x32_bf16 v[16:19], v[204:207], v[228:231], v[16:19]
	v_mfma_f32_16x16x32_bf16 v[4:7], v[194:197], v[236:239], v[4:7]
	v_mfma_f32_16x16x32_bf16 v[0:3], v[204:207], v[236:239], v[0:3]
	s_setprio 0
	s_barrier
	s_add_i32 s39, 0, 0x18000
	s_add_i32 s40, 0, 0x1c000
	v_add_u32_e32 v186, s39, v175
	v_add_u32_e32 v199, s40, v175
	ds_read_b128 v[164:167], v186
	ds_read_b128 v[168:171], v186 offset:1024
	ds_read_b128 v[182:185], v186 offset:2048
	ds_read_b128 v[186:189], v186 offset:3072
	ds_read_b128 v[190:193], v199
	ds_read_b128 v[194:197], v199 offset:1024
	ds_read_b128 v[200:203], v199 offset:2048
	ds_read_b128 v[204:207], v199 offset:3072
	s_add_u32 s30, s30, 0x40000
	s_addc_u32 s31, s31, 0
	s_mov_b32 m0, s73
	v_lshl_add_u64 v[246:247], s[30:31], 0, v[128:129]
	ds_read_b128 v[208:211], v180 offset:32768
	ds_read_b128 v[212:215], v180 offset:33792
	ds_read_b128 v[216:219], v180 offset:34816
	ds_read_b128 v[220:223], v180 offset:35840
	ds_read_b128 v[224:227], v180 offset:36864
	ds_read_b128 v[228:231], v180 offset:37888
	ds_read_b128 v[232:235], v180 offset:38912
	ds_read_b128 v[236:239], v180 offset:39936
	global_load_lds_dwordx4 v[246:247], off
	v_lshl_add_u64 v[246:247], s[30:31], 0, v[132:133]
	s_mov_b32 m0, s74
	s_nop 0
	global_load_lds_dwordx4 v[246:247], off
	s_waitcnt vmcnt(8)
	s_waitcnt lgkmcnt(0)
	s_barrier
	s_setprio 1
	s_waitcnt lgkmcnt(0)
	v_mfma_f32_16x16x32_bf16 v[124:127], v[164:167], v[208:211], v[124:127]
	v_mfma_f32_16x16x32_bf16 v[120:123], v[182:185], v[208:211], v[120:123]
	v_mfma_f32_16x16x32_bf16 v[108:111], v[164:167], v[216:219], v[108:111]
	v_mfma_f32_16x16x32_bf16 v[104:107], v[182:185], v[216:219], v[104:107]
	v_mfma_f32_16x16x32_bf16 v[92:95], v[164:167], v[224:227], v[92:95]
	v_mfma_f32_16x16x32_bf16 v[88:91], v[182:185], v[224:227], v[88:91]
	v_mfma_f32_16x16x32_bf16 v[76:79], v[164:167], v[232:235], v[76:79]
	v_mfma_f32_16x16x32_bf16 v[72:75], v[182:185], v[232:235], v[72:75]
	v_mfma_f32_16x16x32_bf16 v[124:127], v[168:171], v[212:215], v[124:127]
	v_mfma_f32_16x16x32_bf16 v[120:123], v[186:189], v[212:215], v[120:123]
	v_mfma_f32_16x16x32_bf16 v[108:111], v[168:171], v[220:223], v[108:111]
	v_mfma_f32_16x16x32_bf16 v[104:107], v[186:189], v[220:223], v[104:107]
	v_mfma_f32_16x16x32_bf16 v[92:95], v[168:171], v[228:231], v[92:95]
	v_mfma_f32_16x16x32_bf16 v[88:91], v[186:189], v[228:231], v[88:91]
	v_mfma_f32_16x16x32_bf16 v[76:79], v[168:171], v[236:239], v[76:79]
	v_mfma_f32_16x16x32_bf16 v[72:75], v[186:189], v[236:239], v[72:75]
	s_setprio 0
	s_setprio 1
	v_mfma_f32_16x16x32_bf16 v[116:119], v[190:193], v[208:211], v[116:119]
	v_mfma_f32_16x16x32_bf16 v[112:115], v[200:203], v[208:211], v[112:115]
	v_mfma_f32_16x16x32_bf16 v[100:103], v[190:193], v[216:219], v[100:103]
	v_mfma_f32_16x16x32_bf16 v[96:99], v[200:203], v[216:219], v[96:99]
	v_mfma_f32_16x16x32_bf16 v[84:87], v[190:193], v[224:227], v[84:87]
	v_mfma_f32_16x16x32_bf16 v[80:83], v[200:203], v[224:227], v[80:83]
	v_mfma_f32_16x16x32_bf16 v[68:71], v[190:193], v[232:235], v[68:71]
	v_mfma_f32_16x16x32_bf16 v[64:67], v[200:203], v[232:235], v[64:67]
	v_mfma_f32_16x16x32_bf16 v[116:119], v[194:197], v[212:215], v[116:119]
	v_mfma_f32_16x16x32_bf16 v[112:115], v[204:207], v[212:215], v[112:115]
	v_mfma_f32_16x16x32_bf16 v[100:103], v[194:197], v[220:223], v[100:103]
	v_mfma_f32_16x16x32_bf16 v[96:99], v[204:207], v[220:223], v[96:99]
	v_mfma_f32_16x16x32_bf16 v[84:87], v[194:197], v[228:231], v[84:87]
	v_mfma_f32_16x16x32_bf16 v[80:83], v[204:207], v[228:231], v[80:83]
	v_mfma_f32_16x16x32_bf16 v[68:71], v[194:197], v[236:239], v[68:71]
	v_mfma_f32_16x16x32_bf16 v[64:67], v[204:207], v[236:239], v[64:67]
	s_setprio 0
	s_barrier
	s_add_i32 s30, s39, s70
	v_lshl_add_u64 v[172:173], v[172:173], 0, s[8:9]
	s_mov_b32 m0, s30
	ds_read_b128 v[208:211], v180 offset:49152
	ds_read_b128 v[212:215], v180 offset:50176
	ds_read_b128 v[216:219], v180 offset:51200
	ds_read_b128 v[220:223], v180 offset:52224
	ds_read_b128 v[224:227], v180 offset:53248
	ds_read_b128 v[228:231], v180 offset:54272
	ds_read_b128 v[232:235], v180 offset:55296
	ds_read_b128 v[236:239], v180 offset:56320
	global_load_lds_dwordx4 v[172:173], off
	s_add_i32 m0, s30, 0x2000
	s_add_u32 s28, s28, 0x40080
	v_lshl_add_u64 v[172:173], v[240:241], 0, s[8:9]
	s_addc_u32 s29, s29, 0
	s_add_i32 s30, s40, s70
	global_load_lds_dwordx4 v[172:173], off
	v_lshl_add_u64 v[172:173], s[28:29], 0, v[130:131]
	s_mov_b32 m0, s30
	s_nop 0
	global_load_lds_dwordx4 v[172:173], off
	v_lshl_add_u64 v[172:173], s[28:29], 0, v[134:135]
	s_add_i32 m0, s30, 0x2000
	s_nop 0
	global_load_lds_dwordx4 v[172:173], off
	v_lshl_add_u64 v[172:173], v[242:243], 0, s[8:9]
	s_mov_b32 m0, s76
	s_nop 0
	global_load_lds_dwordx4 v[172:173], off
	v_lshl_add_u64 v[172:173], v[244:245], 0, s[8:9]
	s_mov_b32 m0, s77
	s_nop 0
	global_load_lds_dwordx4 v[172:173], off
	s_waitcnt vmcnt(8)
	s_waitcnt lgkmcnt(0)
	s_barrier
	s_setprio 1
	s_waitcnt lgkmcnt(0)
	v_mfma_f32_16x16x32_bf16 v[60:63], v[164:167], v[208:211], v[60:63]
	v_mfma_f32_16x16x32_bf16 v[56:59], v[182:185], v[208:211], v[56:59]
	v_mfma_f32_16x16x32_bf16 v[44:47], v[164:167], v[216:219], v[44:47]
	v_mfma_f32_16x16x32_bf16 v[40:43], v[182:185], v[216:219], v[40:43]
	v_mfma_f32_16x16x32_bf16 v[28:31], v[164:167], v[224:227], v[28:31]
	v_mfma_f32_16x16x32_bf16 v[24:27], v[182:185], v[224:227], v[24:27]
	v_mfma_f32_16x16x32_bf16 v[12:15], v[164:167], v[232:235], v[12:15]
	v_mfma_f32_16x16x32_bf16 v[8:11], v[182:185], v[232:235], v[8:11]
	v_mfma_f32_16x16x32_bf16 v[60:63], v[168:171], v[212:215], v[60:63]
	v_mfma_f32_16x16x32_bf16 v[56:59], v[186:189], v[212:215], v[56:59]
	v_mfma_f32_16x16x32_bf16 v[44:47], v[168:171], v[220:223], v[44:47]
	v_mfma_f32_16x16x32_bf16 v[40:43], v[186:189], v[220:223], v[40:43]
	v_mfma_f32_16x16x32_bf16 v[28:31], v[168:171], v[228:231], v[28:31]
	v_mfma_f32_16x16x32_bf16 v[24:27], v[186:189], v[228:231], v[24:27]
	v_mfma_f32_16x16x32_bf16 v[12:15], v[168:171], v[236:239], v[12:15]
	v_mfma_f32_16x16x32_bf16 v[8:11], v[186:189], v[236:239], v[8:11]
	s_setprio 0
	s_setprio 1
	v_mfma_f32_16x16x32_bf16 v[52:55], v[190:193], v[208:211], v[52:55]
	v_mfma_f32_16x16x32_bf16 v[48:51], v[200:203], v[208:211], v[48:51]
	v_mfma_f32_16x16x32_bf16 v[36:39], v[190:193], v[216:219], v[36:39]
	v_mfma_f32_16x16x32_bf16 v[32:35], v[200:203], v[216:219], v[32:35]
	v_mfma_f32_16x16x32_bf16 v[20:23], v[190:193], v[224:227], v[20:23]
	v_mfma_f32_16x16x32_bf16 v[16:19], v[200:203], v[224:227], v[16:19]
	v_mfma_f32_16x16x32_bf16 v[4:7], v[190:193], v[232:235], v[4:7]
	v_mfma_f32_16x16x32_bf16 v[0:3], v[200:203], v[232:235], v[0:3]
	v_mfma_f32_16x16x32_bf16 v[52:55], v[194:197], v[212:215], v[52:55]
	v_mfma_f32_16x16x32_bf16 v[48:51], v[204:207], v[212:215], v[48:51]
	v_mfma_f32_16x16x32_bf16 v[36:39], v[194:197], v[220:223], v[36:39]
	v_mfma_f32_16x16x32_bf16 v[32:35], v[204:207], v[220:223], v[32:35]
	v_mfma_f32_16x16x32_bf16 v[20:23], v[194:197], v[228:231], v[20:23]
	v_mfma_f32_16x16x32_bf16 v[16:19], v[204:207], v[228:231], v[16:19]
	v_mfma_f32_16x16x32_bf16 v[4:7], v[194:197], v[236:239], v[4:7]
	v_mfma_f32_16x16x32_bf16 v[0:3], v[204:207], v[236:239], v[0:3]
	s_setprio 0
	s_barrier
	s_add_i32 s38, s38, 2
	s_add_u32 s26, s26, 0x100
	s_addc_u32 s27, s27, 0
	s_add_u32 s36, s36, 0x100
	s_addc_u32 s37, s37, 0
	s_cmp_gt_u32 s38, 13
	s_cbranch_scc0 .LBB0_157
	s_and_b64 vcc, exec, s[10:11]
	s_cbranch_vccz .LBB0_160
	s_barrier

.LBB0_416:
	v_mov_b32_e32 v1, v198
	s_load_dwordx8 s[4:11], s[0:1], 0x48
	v_and_b32_e32 v0, 63, v1
	v_lshlrev_b32_e32 v2, 2, v0
	s_cmpk_gt_i32 s3, 0x3ff
	s_waitcnt lgkmcnt(0)
	global_load_dword v3, v2, s[4:5]
	global_load_dword v4, v2, s[6:7]
	global_load_dword v5, v2, s[8:9]
	global_load_dword v6, v2, s[10:11]
	v_mbcnt_hi_u32_b32 v2, -1, v178
	v_and_b32_e32 v7, 64, v2
	v_xor_b32_e32 v8, 1, v2
	v_add_u32_e32 v7, 64, v7
	v_cmp_lt_i32_e32 vcc, v8, v7
	v_xor_b32_e32 v9, 2, v2
	v_xor_b32_e32 v10, 4, v2
	v_cndmask_b32_e32 v8, v2, v8, vcc
	v_lshlrev_b32_e32 v199, 2, v8
	v_cmp_lt_i32_e32 vcc, v9, v7
	v_xor_b32_e32 v11, 8, v2
	v_xor_b32_e32 v12, 16, v2
	v_cndmask_b32_e32 v9, v2, v9, vcc
	v_lshlrev_b32_e32 v200, 2, v9
	v_cmp_lt_i32_e32 vcc, v10, v7
	v_xor_b32_e32 v13, 32, v2
	v_readfirstlane_b32 s4, v1
	s_mov_b32 s21, 0
	s_waitcnt vmcnt(2)
	v_mul_f32_e32 v8, v3, v4
	ds_bpermute_b32 v8, v199, v8
	s_waitcnt vmcnt(0)
	v_mul_f32_e32 v14, v5, v6
	ds_bpermute_b32 v14, v199, v14
	s_waitcnt lgkmcnt(1)
	v_fmac_f32_e32 v8, v3, v4
	ds_bpermute_b32 v3, v200, v8
	s_waitcnt lgkmcnt(1)
	v_fmac_f32_e32 v14, v5, v6
	ds_bpermute_b32 v4, v200, v14
	v_cndmask_b32_e32 v5, v2, v10, vcc
	v_lshlrev_b32_e32 v201, 2, v5
	s_waitcnt lgkmcnt(1)
	v_add_f32_e32 v3, v8, v3
	ds_bpermute_b32 v5, v201, v3
	s_waitcnt lgkmcnt(1)
	v_add_f32_e32 v4, v14, v4
	ds_bpermute_b32 v6, v201, v4
	v_cmp_lt_i32_e32 vcc, v11, v7
	s_waitcnt lgkmcnt(1)
	v_add_f32_e32 v3, v3, v5
	v_cndmask_b32_e32 v8, v2, v11, vcc
	v_lshlrev_b32_e32 v202, 2, v8
	s_waitcnt lgkmcnt(0)
	v_add_f32_e32 v4, v4, v6
	ds_bpermute_b32 v5, v202, v3
	ds_bpermute_b32 v6, v202, v4
	v_cmp_lt_i32_e32 vcc, v12, v7
	s_waitcnt lgkmcnt(1)
	v_add_f32_e32 v3, v3, v5
	v_cndmask_b32_e32 v8, v2, v12, vcc
	v_lshlrev_b32_e32 v203, 2, v8
	s_waitcnt lgkmcnt(0)
	v_add_f32_e32 v4, v4, v6
	ds_bpermute_b32 v5, v203, v3
	ds_bpermute_b32 v6, v203, v4
	v_cmp_lt_i32_e32 vcc, v13, v7
	s_nop 1
	v_cndmask_b32_e32 v2, v2, v13, vcc
	v_lshlrev_b32_e32 v204, 2, v2
	s_waitcnt lgkmcnt(1)
	v_add_f32_e32 v2, v3, v5
	s_waitcnt lgkmcnt(0)
	v_add_f32_e32 v3, v4, v6
	ds_bpermute_b32 v4, v204, v2
	ds_bpermute_b32 v5, v204, v3
	s_cbranch_scc1 .LBB0_436
	s_waitcnt lgkmcnt(1)
	v_add_f32_e32 v2, v2, v4
	s_waitcnt lgkmcnt(0)
	v_add_f32_e32 v3, v3, v5
	s_load_dwordx2 s[88:89], s[0:1], 0x68
	v_lshlrev_b32_e32 v250, 4, v198
	v_cmp_gt_u32_e32 vcc, 32, v198
	s_waitcnt lgkmcnt(0)
	s_and_saveexec_b64 s[90:91], vcc
	global_load_dwordx4 v[252:255], v250, s[88:89]
	v_add_u32_e32 v250, 0x1f000, v250
	s_waitcnt vmcnt(0)
	ds_write_b128 v250, v[252:255]
	s_or_b64 exec, exec, s[90:91]
	s_waitcnt lgkmcnt(0)
	s_ashr_i32 s4, s4, 6
	v_mul_f32_e32 v2, 0x3fb8aa3b, v2
	v_mul_f32_e32 v3, 0x3fb8aa3b, v3
	s_lshl_b32 s5, s4, 3
	v_lshrrev_b32_e32 v4, 3, v0
	v_exp_f32_e32 v2, v2
	v_exp_f32_e32 v3, v3
	v_or_b32_e32 v5, s5, v4
	v_lshrrev_b32_e32 v7, 4, v0
	v_lshrrev_b32_e32 v6, 1, v5
	v_or_b32_e32 v8, s5, v7
	v_lshlrev_b32_e32 v7, 2, v7
	v_xor_b32_e32 v6, v6, v1
	v_bitop3_b32 v7, v7, v1, 12 bitop3:0x78
	v_lshlrev_b32_e32 v6, 3, v6
	v_and_or_b32 v7, v1, 3, v7
	v_lshlrev_b32_e32 v8, 10, v8
	v_lshlrev_b32_e32 v5, 10, v5
	v_sub_f32_e32 v2, v2, v3
	v_lshrrev_b32_e32 v3, 5, v0
	v_lshl_or_b32 v176, v7, 3, v8
	v_and_b32_e32 v7, 31, v1
	v_and_or_b32 v180, v6, 56, v5
	v_lshrrev_b32_e32 v6, 1, v1
	v_lshlrev_b32_e32 v5, 7, v7
	v_bfe_u32 v8, v1, 1, 3
	v_bitop3_b32 v6, v3, v6, 7 bitop3:0x78
	v_lshl_or_b32 v206, v6, 4, v5
	v_bitop3_b32 v6, v3, v8, 2 bitop3:0x36
	v_lshl_or_b32 v207, v6, 4, v5
	v_bitop3_b32 v6, v3, v8, 4 bitop3:0x36
	s_lshl_b32 s40, s4, 5
	v_lshl_or_b32 v208, v6, 4, v5
	v_bitop3_b32 v6, v3, v8, 6 bitop3:0x36
	s_lshl_b32 s42, s4, 10
	v_bfe_u32 v1, v1, 2, 2
	s_lshl_b32 s4, s4, 13
	v_lshl_or_b32 v209, v6, 4, v5
	v_and_or_b32 v4, v4, 4, v1
	v_lshlrev_b32_e32 v5, 1, v0
	v_lshlrev_b32_e32 v6, 3, v0
	s_add_i32 s4, s4, 0
	s_add_i32 s43, s42, 0
	v_lshlrev_b32_e32 v4, 8, v4
	v_and_b32_e32 v5, 32, v5
	v_and_b32_e32 v6, 24, v6
	v_lshl_add_u32 v210, v0, 2, s4
	v_lshlrev_b32_e32 v0, 4, v3
	s_add_i32 s4, s43, s42
	v_or3_b32 v4, v4, v5, v6
	v_lshlrev_b32_e32 v5, 6, v1
	v_lshl_or_b32 v0, v7, 11, v0
	v_mov_b32_e32 v1, 0
	s_add_i32 s65, s4, 0x6000
	s_add_i32 s66, s4, 0x6400
	s_add_i32 s67, s4, 0xa000
	s_add_i32 s68, s4, 0xa400
	s_movk_i32 s4, 0x80
	s_ashr_i32 s41, s40, 31
	v_lshl_add_u64 v[182:183], s[58:59], 0, v[0:1]
	v_mov_b32_e32 v181, v1
	s_add_i32 s64, s43, 0x2000
	v_lshl_add_u64 v[184:185], s[62:63], 0, v[0:1]
	v_mov_b32_e32 v177, v1
	v_mov_b32_e32 v179, v1
	v_bitop3_b32 v1, v4, s4, v5 bitop3:0x36
	s_movk_i32 s4, 0xc0
	v_add_f32_e32 v205, 0x3e4ccccd, v2
	v_lshlrev_b32_e32 v2, 3, v3
	v_or_b32_e32 v6, v4, v5
	v_bitop3_b32 v0, v4, 64, v5 bitop3:0x36
	v_bitop3_b32 v3, v4, s4, v5 bitop3:0x36
	s_add_u32 s62, s44, 0x16820000
	v_or_b32_e32 v178, 0x1000, v176
	s_addc_u32 s63, s45, 0
	s_lshl_b32 s69, s3, 4
	s_lshl_b32 s70, s46, 4
	s_mov_b64 s[22:23], 0x20000
	s_movk_i32 s71, 0x4000
	s_mov_b64 s[24:25], 0x60000
	v_mov_b32_e32 v211, 0x358637bd
	s_mov_b32 s72, 0x800000
	v_lshlrev_b32_e32 v212, 2, v2
	v_add_u32_e32 v251, 0x1f000, v212
	v_add_u32_e32 v213, 0, v6
	v_add_u32_e32 v214, 0, v0
	v_add_u32_e32 v215, 0, v1
	v_add_u32_e32 v216, 0, v3
	s_branch .LBB0_419

.LBB0_432:
	ds_bpermute_b32 v64, v204, v196
	s_mov_b64 s[6:7], -1
	s_waitcnt lgkmcnt(0)
	v_add_f32_e32 v64, v196, v64
	v_div_scale_f32 v65, s[4:5], v64, v64, 1.0
	v_rcp_f32_e32 v66, v65
	v_div_scale_f32 v67, vcc, 1.0, v64, 1.0
	s_and_b64 s[4:5], exec, s[30:31]
	v_fma_f32 v68, -v65, v66, 1.0
	v_fmac_f32_e32 v66, v68, v66
	v_mul_f32_e32 v68, v67, v66
	v_fma_f32 v69, -v65, v68, v67
	v_fmac_f32_e32 v68, v69, v66
	v_fma_f32 v65, -v65, v68, v67
	v_div_fmas_f32 v65, v65, v66, v68
	v_div_fixup_f32 v64, v65, v64, 1.0
	s_mov_b64 vcc, s[4:5]
	s_cbranch_vccz .LBB0_434
	global_load_dwordx4 v[116:119], v[188:189], off
	global_load_dwordx4 v[120:123], v[188:189], off offset:32
	global_load_dwordx4 v[124:127], v[188:189], off offset:64
	global_load_dwordx4 v[128:131], v[188:189], off offset:96
	global_load_dwordx4 v[132:135], v[188:189], off offset:128
	global_load_dwordx4 v[136:139], v[188:189], off offset:160
	global_load_dwordx4 v[140:143], v[188:189], off offset:192
	global_load_dwordx4 v[144:147], v[188:189], off offset:224
	ds_read2st64_b32 v[68:69], v210 offset0:224 offset1:225
	v_mul_f32_e32 v66, v205, v64
	ds_read2st64_b32 v[70:71], v210 offset0:226 offset1:227
	ds_read2st64_b32 v[72:73], v210 offset0:228 offset1:229
	ds_read2st64_b32 v[74:75], v210 offset0:230 offset1:231
	v_mov_b32_e32 v88, v29
	s_waitcnt lgkmcnt(3)
	v_and_b32_e32 v67, 0xffff0000, v68
	v_lshlrev_b32_e32 v65, 16, v68
	v_fma_f32 v67, -v49, v66, v67
	v_fma_f32 v65, -v48, v66, v65
	v_mul_f32_e32 v67, v67, v67
	v_and_b32_e32 v68, 0xffff0000, v69
	v_fmac_f32_e32 v67, v65, v65
	v_lshlrev_b32_e32 v65, 16, v69
	v_fma_f32 v68, -v51, v66, v68
	v_fma_f32 v65, -v50, v66, v65
	v_mul_f32_e32 v68, v68, v68
	v_fmac_f32_e32 v68, v65, v65
	v_add_f32_e32 v65, v67, v68
	s_waitcnt lgkmcnt(2)
	v_and_b32_e32 v68, 0xffff0000, v70
	v_lshlrev_b32_e32 v67, 16, v70
	v_fma_f32 v68, -v53, v66, v68
	v_fma_f32 v67, -v52, v66, v67
	v_mul_f32_e32 v68, v68, v68
	v_fmac_f32_e32 v68, v67, v67
	v_add_f32_e32 v65, v65, v68
	v_and_b32_e32 v68, 0xffff0000, v71
	v_lshlrev_b32_e32 v67, 16, v71
	v_fma_f32 v68, -v55, v66, v68
	v_fma_f32 v67, -v54, v66, v67
	v_mul_f32_e32 v68, v68, v68
	v_fmac_f32_e32 v68, v67, v67
	v_add_f32_e32 v65, v65, v68
	s_waitcnt lgkmcnt(1)
	v_and_b32_e32 v68, 0xffff0000, v72
	v_lshlrev_b32_e32 v67, 16, v72
	v_fma_f32 v68, -v57, v66, v68
	v_fma_f32 v67, -v56, v66, v67
	v_mul_f32_e32 v68, v68, v68
	v_fmac_f32_e32 v68, v67, v67
	v_add_f32_e32 v65, v65, v68
	v_and_b32_e32 v68, 0xffff0000, v73
	v_lshlrev_b32_e32 v67, 16, v73
	v_fma_f32 v68, -v59, v66, v68
	v_fma_f32 v67, -v58, v66, v67
	v_mul_f32_e32 v68, v68, v68
	v_fmac_f32_e32 v68, v67, v67
	v_add_f32_e32 v65, v65, v68
	s_waitcnt lgkmcnt(0)
	v_and_b32_e32 v68, 0xffff0000, v74
	v_lshlrev_b32_e32 v67, 16, v74
	v_fma_f32 v68, -v61, v66, v68
	v_fma_f32 v67, -v60, v66, v67
	v_mul_f32_e32 v68, v68, v68
	v_fmac_f32_e32 v68, v67, v67
	v_add_f32_e32 v65, v65, v68
	v_and_b32_e32 v68, 0xffff0000, v75
	v_fma_f32 v68, -v63, v66, v68
	v_mul_f32_e32 v70, v68, v68
	ds_read2st64_b32 v[68:69], v210 offset0:232 offset1:233
	v_lshlrev_b32_e32 v67, 16, v75
	v_fma_f32 v67, -v62, v66, v67
	v_fmac_f32_e32 v70, v67, v67
	v_add_f32_e32 v65, v65, v70
	s_waitcnt lgkmcnt(0)
	v_lshlrev_b32_e32 v67, 16, v68
	v_and_b32_e32 v68, 0xffff0000, v68
	v_fma_f32 v68, -v33, v66, v68
	v_fma_f32 v67, -v32, v66, v67
	v_mul_f32_e32 v68, v68, v68
	v_fmac_f32_e32 v68, v67, v67
	v_add_f32_e32 v65, v65, v68
	v_and_b32_e32 v68, 0xffff0000, v69
	ds_read2st64_b32 v[70:71], v210 offset0:234 offset1:235
	ds_read2st64_b32 v[72:73], v210 offset0:236 offset1:237
	ds_read2st64_b32 v[74:75], v210 offset0:238 offset1:239
	v_lshlrev_b32_e32 v67, 16, v69
	v_fma_f32 v68, -v35, v66, v68
	v_fma_f32 v67, -v34, v66, v67
	v_mul_f32_e32 v68, v68, v68
	v_fmac_f32_e32 v68, v67, v67
	v_add_f32_e32 v65, v65, v68
	s_waitcnt lgkmcnt(2)
	v_and_b32_e32 v68, 0xffff0000, v70
	v_lshlrev_b32_e32 v67, 16, v70
	v_fma_f32 v68, -v37, v66, v68
	v_fma_f32 v67, -v36, v66, v67
	v_mul_f32_e32 v68, v68, v68
	v_fmac_f32_e32 v68, v67, v67
	v_add_f32_e32 v65, v65, v68
	v_and_b32_e32 v68, 0xffff0000, v71
	v_lshlrev_b32_e32 v67, 16, v71
	v_fma_f32 v68, -v39, v66, v68
	v_fma_f32 v67, -v38, v66, v67
	v_mul_f32_e32 v68, v68, v68
	v_fmac_f32_e32 v68, v67, v67
	v_add_f32_e32 v65, v65, v68
	s_waitcnt lgkmcnt(1)
	v_and_b32_e32 v68, 0xffff0000, v72
	v_lshlrev_b32_e32 v67, 16, v72
	v_fma_f32 v68, -v41, v66, v68
	v_fma_f32 v67, -v40, v66, v67
	v_mul_f32_e32 v68, v68, v68
	v_fmac_f32_e32 v68, v67, v67
	v_add_f32_e32 v65, v65, v68
	v_and_b32_e32 v68, 0xffff0000, v73
	v_lshlrev_b32_e32 v67, 16, v73
	v_fma_f32 v68, -v43, v66, v68
	v_fma_f32 v67, -v42, v66, v67
	v_mul_f32_e32 v68, v68, v68
	v_fmac_f32_e32 v68, v67, v67
	v_add_f32_e32 v65, v65, v68
	s_waitcnt lgkmcnt(0)
	v_and_b32_e32 v68, 0xffff0000, v74
	v_lshlrev_b32_e32 v67, 16, v74
	v_fma_f32 v68, -v45, v66, v68
	v_fma_f32 v67, -v44, v66, v67
	v_mul_f32_e32 v68, v68, v68
	v_fmac_f32_e32 v68, v67, v67
	v_add_f32_e32 v65, v65, v68
	v_and_b32_e32 v68, 0xffff0000, v75
	v_fma_f32 v68, -v47, v66, v68
	v_mul_f32_e32 v70, v68, v68
	ds_read2st64_b32 v[68:69], v210 offset0:240 offset1:241
	v_lshlrev_b32_e32 v67, 16, v75
	v_fma_f32 v67, -v46, v66, v67
	v_fmac_f32_e32 v70, v67, v67
	v_add_f32_e32 v65, v65, v70
	s_waitcnt lgkmcnt(0)
	v_lshlrev_b32_e32 v67, 16, v68
	v_and_b32_e32 v68, 0xffff0000, v68
	v_fma_f32 v68, -v17, v66, v68
	v_fma_f32 v67, -v16, v66, v67
	v_mul_f32_e32 v68, v68, v68
	v_fmac_f32_e32 v68, v67, v67
	v_add_f32_e32 v65, v65, v68
	v_and_b32_e32 v68, 0xffff0000, v69
	ds_read2st64_b32 v[70:71], v210 offset0:242 offset1:243
	ds_read2st64_b32 v[72:73], v210 offset0:244 offset1:245
	ds_read2st64_b32 v[74:75], v210 offset0:246 offset1:247
	v_lshlrev_b32_e32 v67, 16, v69
	v_fma_f32 v68, -v19, v66, v68
	v_fma_f32 v67, -v18, v66, v67
	v_mul_f32_e32 v68, v68, v68
	v_fmac_f32_e32 v68, v67, v67
	v_add_f32_e32 v65, v65, v68
	s_waitcnt lgkmcnt(2)
	v_and_b32_e32 v68, 0xffff0000, v70
	v_lshlrev_b32_e32 v67, 16, v70
	v_fma_f32 v68, -v21, v66, v68
	v_fma_f32 v67, -v20, v66, v67
	v_mul_f32_e32 v68, v68, v68
	v_fmac_f32_e32 v68, v67, v67
	v_add_f32_e32 v65, v65, v68
	v_and_b32_e32 v68, 0xffff0000, v71
	v_lshlrev_b32_e32 v67, 16, v71
	v_fma_f32 v68, -v23, v66, v68
	v_fma_f32 v67, -v22, v66, v67
	v_mul_f32_e32 v68, v68, v68
	v_fmac_f32_e32 v68, v67, v67
	v_add_f32_e32 v65, v65, v68
	s_waitcnt lgkmcnt(1)
	v_and_b32_e32 v68, 0xffff0000, v72
	v_lshlrev_b32_e32 v67, 16, v72
	v_fma_f32 v68, -v25, v66, v68
	v_fma_f32 v67, -v24, v66, v67
	v_mul_f32_e32 v68, v68, v68
	v_fmac_f32_e32 v68, v67, v67
	v_add_f32_e32 v65, v65, v68
	v_and_b32_e32 v68, 0xffff0000, v73
	v_lshlrev_b32_e32 v67, 16, v73
	v_fma_f32 v68, -v27, v66, v68
	v_fma_f32 v67, -v26, v66, v67
	v_mul_f32_e32 v68, v68, v68
	v_fmac_f32_e32 v68, v67, v67
	s_waitcnt lgkmcnt(0)
	v_and_b32_e32 v71, 0xffff0000, v75
	v_and_b32_e32 v70, 0xffff0000, v74
	v_mov_b32_e32 v89, v31
	v_add_f32_e32 v65, v65, v68
	v_lshlrev_b32_e32 v69, 16, v75
	v_lshlrev_b32_e32 v68, 16, v74
	v_mov_b32_e32 v86, v28
	v_mov_b32_e32 v87, v30
	v_pk_fma_f32 v[70:71], v[88:89], v[66:67], v[70:71] op_sel_hi:[1,0,1] neg_lo:[1,0,0] neg_hi:[1,0,0]
	v_pk_fma_f32 v[68:69], v[86:87], v[66:67], v[68:69] op_sel_hi:[1,0,1] neg_lo:[1,0,0] neg_hi:[1,0,0]
	v_pk_mul_f32 v[70:71], v[70:71], v[70:71]
	v_mov_b32_e32 v80, v1
	v_pk_fma_f32 v[68:69], v[68:69], v[68:69], v[70:71]
	ds_read2st64_b32 v[70:71], v210 offset0:248 offset1:249
	v_add_f32_e32 v65, v65, v68
	v_add_f32_e32 v65, v65, v69
	ds_read2st64_b32 v[68:69], v210 offset0:250 offset1:251
	ds_read2st64_b32 v[72:73], v210 offset0:252 offset1:253
	ds_read2st64_b32 v[76:77], v210 offset0:254 offset1:255
	s_waitcnt vmcnt(0)
	s_nop 1
	v_mov_b32_e32 v90, v116
	v_mov_b32_e32 v91, v117
	v_mov_b32_e32 v92, v118
	v_mov_b32_e32 v93, v119
	s_load_dwordx2 s[4:5], s[0:1], 0x68
	s_waitcnt lgkmcnt(0)
	v_lshlrev_b32_e32 v75, 16, v71
	v_lshlrev_b32_e32 v74, 16, v70
	v_and_b32_e32 v71, 0xffff0000, v71
	v_and_b32_e32 v70, 0xffff0000, v70
	v_mov_b32_e32 v81, v3
	v_mov_b32_e32 v78, v0
	v_mov_b32_e32 v79, v2
	v_pk_fma_f32 v[70:71], v[80:81], v[66:67], v[70:71] op_sel_hi:[1,0,1] neg_lo:[1,0,0] neg_hi:[1,0,0]
	v_pk_fma_f32 v[74:75], v[78:79], v[66:67], v[74:75] op_sel_hi:[1,0,1] neg_lo:[1,0,0] neg_hi:[1,0,0]
	v_pk_mul_f32 v[70:71], v[70:71], v[70:71]
	ds_read_b128 v[94:97], v251
	v_pk_fma_f32 v[70:71], v[74:75], v[74:75], v[70:71]
	v_mov_b32_e32 v84, v5
	v_add_f32_e32 v65, v65, v70
	v_add_f32_e32 v65, v65, v71
	v_lshlrev_b32_e32 v71, 16, v69
	v_lshlrev_b32_e32 v70, 16, v68
	v_and_b32_e32 v69, 0xffff0000, v69
	v_and_b32_e32 v68, 0xffff0000, v68
	v_mov_b32_e32 v85, v7
	v_mov_b32_e32 v82, v4
	v_mov_b32_e32 v83, v6
	v_pk_fma_f32 v[68:69], v[84:85], v[66:67], v[68:69] op_sel_hi:[1,0,1] neg_lo:[1,0,0] neg_hi:[1,0,0]
	v_pk_fma_f32 v[70:71], v[82:83], v[66:67], v[70:71] op_sel_hi:[1,0,1] neg_lo:[1,0,0] neg_hi:[1,0,0]
	v_pk_mul_f32 v[68:69], v[68:69], v[68:69]
	v_and_b32_e32 v75, 0xffff0000, v73
	v_pk_fma_f32 v[68:69], v[70:71], v[70:71], v[68:69]
	v_and_b32_e32 v74, 0xffff0000, v72
	v_add_f32_e32 v65, v65, v68
	v_add_f32_e32 v65, v65, v69
	v_lshlrev_b32_e32 v69, 16, v73
	v_lshlrev_b32_e32 v68, 16, v72
	v_mov_b32_e32 v72, v9
	v_mov_b32_e32 v73, v11
	v_mov_b32_e32 v70, v8
	v_mov_b32_e32 v71, v10
	v_pk_fma_f32 v[74:75], v[72:73], v[66:67], v[74:75] op_sel_hi:[1,0,1] neg_lo:[1,0,0] neg_hi:[1,0,0]
	v_pk_fma_f32 v[68:69], v[70:71], v[66:67], v[68:69] op_sel_hi:[1,0,1] neg_lo:[1,0,0] neg_hi:[1,0,0]
	v_pk_mul_f32 v[74:75], v[74:75], v[74:75]
	v_and_b32_e32 v99, 0xffff0000, v77
	v_pk_fma_f32 v[68:69], v[68:69], v[68:69], v[74:75]
	v_and_b32_e32 v98, 0xffff0000, v76
	v_add_f32_e32 v65, v65, v68
	v_add_f32_e32 v65, v65, v69
	v_lshlrev_b32_e32 v69, 16, v77
	v_lshlrev_b32_e32 v68, 16, v76
	v_mov_b32_e32 v76, v13
	v_mov_b32_e32 v77, v15
	v_mov_b32_e32 v74, v12
	v_mov_b32_e32 v75, v14
	v_pk_fma_f32 v[98:99], v[76:77], v[66:67], v[98:99] op_sel_hi:[1,0,1] neg_lo:[1,0,0] neg_hi:[1,0,0]
	v_pk_fma_f32 v[68:69], v[74:75], v[66:67], v[68:69] op_sel_hi:[1,0,1] neg_lo:[1,0,0] neg_hi:[1,0,0]
	v_pk_mul_f32 v[98:99], v[98:99], v[98:99]
	ds_read2st64_b32 v[102:103], v210 offset0:224 offset1:225
	ds_read2st64_b32 v[104:105], v210 offset0:226 offset1:227
	v_pk_fma_f32 v[68:69], v[68:69], v[68:69], v[98:99]
	ds_read_b128 v[98:101], v251 offset:16
	v_add_f32_e32 v65, v65, v68
	v_add_f32_e32 v65, v65, v69
	ds_bpermute_b32 v67, v204, v65
	s_waitcnt lgkmcnt(0)
	v_add_f32_e32 v65, v65, v67
	v_fmamk_f32 v65, v65, 0x3c000000, v211
	v_mul_f32_e32 v67, 0x4b800000, v65
	v_cmp_gt_f32_e32 vcc, s72, v65
	v_lshlrev_b32_e32 v110, 16, v90
	v_cndmask_b32_e32 v65, v65, v67, vcc
	v_rsq_f32_e32 v65, v65
	v_and_b32_e32 v111, 0xffff0000, v90
	v_mul_f32_e32 v67, 0x45800000, v65
	v_cndmask_b32_e32 v65, v65, v67, vcc
	v_mul_f32_e32 v68, 0x3f4ccccd, v65
	v_lshlrev_b32_e32 v65, 16, v102
	v_fma_f32 v106, -v48, v66, v65
	v_and_b32_e32 v65, 0xffff0000, v102
	v_fma_f32 v107, -v49, v66, v65
	v_lshlrev_b32_e32 v65, 16, v104
	v_fma_f32 v108, -v52, v66, v65
	v_and_b32_e32 v65, 0xffff0000, v104
	v_fma_f32 v109, -v53, v66, v65
	v_lshlrev_b32_e32 v65, 16, v103
	v_fma_f32 v102, -v50, v66, v65
	v_and_b32_e32 v65, 0xffff0000, v103
	v_fma_f32 v103, -v51, v66, v65
	v_lshlrev_b32_e32 v65, 16, v105
	v_fma_f32 v104, -v54, v66, v65
	v_and_b32_e32 v65, 0xffff0000, v105
	v_fma_f32 v105, -v55, v66, v65
	v_mul_f32_e32 v65, 0xbfb8aa3b, v110
	v_exp_f32_e32 v65, v65
	v_mul_f32_e32 v67, 0xbfb8aa3b, v111
	v_exp_f32_e32 v67, v67
	v_permlane32_swap_b32_e32 v106, v108
	v_add_f32_e32 v65, 1.0, v65
	v_rcp_f32_e32 v112, v65
	v_add_f32_e32 v65, 1.0, v67
	v_rcp_f32_e32 v113, v65
	v_permlane32_swap_b32_e32 v107, v109
	v_pk_mul_f32 v[106:107], v[68:69], v[106:107] op_sel_hi:[0,1]
	v_pk_mul_f32 v[94:95], v[94:95], v[106:107]
	v_pk_mul_f32 v[106:107], v[112:113], v[110:111]
	v_lshlrev_b32_e32 v110, 16, v91
	v_and_b32_e32 v111, 0xffff0000, v91
	v_mul_f32_e32 v65, 0xbfb8aa3b, v110
	v_exp_f32_e32 v65, v65
	v_mul_f32_e32 v67, 0xbfb8aa3b, v111
	v_exp_f32_e32 v67, v67
	v_permlane32_swap_b32_e32 v102, v104
	v_permlane32_swap_b32_e32 v103, v105
	v_add_f32_e32 v65, 1.0, v65
	v_pk_mul_f32 v[90:91], v[94:95], v[106:107]
	v_rcp_f32_e32 v94, v65
	v_add_f32_e32 v65, 1.0, v67
	v_pk_mul_f32 v[102:103], v[68:69], v[102:103] op_sel_hi:[0,1]
	v_rcp_f32_e32 v95, v65
	v_pk_mul_f32 v[96:97], v[96:97], v[102:103]
	v_lshlrev_b32_e32 v102, 16, v92
	v_and_b32_e32 v103, 0xffff0000, v92
	v_mul_f32_e32 v65, 0xbfb8aa3b, v102
	v_exp_f32_e32 v65, v65
	v_mul_f32_e32 v67, 0xbfb8aa3b, v103
	v_exp_f32_e32 v67, v67
	v_pk_mul_f32 v[94:95], v[94:95], v[110:111]
	v_cvt_pk_bf16_f32 v90, v90, v91
	v_pk_mul_f32 v[94:95], v[96:97], v[94:95]
	v_add_f32_e32 v65, 1.0, v65
	v_cvt_pk_bf16_f32 v91, v94, v95
	v_pk_mul_f32 v[94:95], v[68:69], v[108:109] op_sel_hi:[0,1]
	v_rcp_f32_e32 v96, v65
	v_add_f32_e32 v65, 1.0, v67
	v_pk_mul_f32 v[94:95], v[98:99], v[94:95]
	v_lshlrev_b32_e32 v98, 16, v93
	v_rcp_f32_e32 v97, v65
	v_and_b32_e32 v99, 0xffff0000, v93
	v_mul_f32_e32 v65, 0xbfb8aa3b, v98
	v_exp_f32_e32 v65, v65
	v_mul_f32_e32 v67, 0xbfb8aa3b, v99
	v_exp_f32_e32 v67, v67
	v_pk_mul_f32 v[96:97], v[96:97], v[102:103]
	v_add_f32_e32 v65, 1.0, v65
	v_pk_mul_f32 v[92:93], v[94:95], v[96:97]
	v_rcp_f32_e32 v94, v65
	v_add_f32_e32 v65, 1.0, v67
	v_rcp_f32_e32 v95, v65
	v_pk_mul_f32 v[96:97], v[68:69], v[104:105] op_sel_hi:[0,1]
	v_pk_mul_f32 v[96:97], v[100:101], v[96:97]
	v_cvt_pk_bf16_f32 v92, v92, v93
	v_pk_mul_f32 v[94:95], v[94:95], v[98:99]
	s_nop 0
	v_pk_mul_f32 v[94:95], v[96:97], v[94:95]
	s_nop 0
	v_cvt_pk_bf16_f32 v93, v94, v95
	global_store_dwordx4 v[186:187], v[90:93], off
	s_nop 1
	v_mov_b32_e32 v90, v120
	v_mov_b32_e32 v91, v121
	v_mov_b32_e32 v92, v122
	v_mov_b32_e32 v93, v123
	ds_read_b128 v[94:97], v251 offset:64
	ds_read_b128 v[98:101], v251 offset:80
	ds_read2st64_b32 v[102:103], v210 offset0:228 offset1:229
	ds_read2st64_b32 v[104:105], v210 offset0:230 offset1:231
	s_waitcnt lgkmcnt(1)
	v_lshlrev_b32_e32 v65, 16, v102
	v_fma_f32 v106, -v56, v66, v65
	v_and_b32_e32 v65, 0xffff0000, v102
	v_fma_f32 v107, -v57, v66, v65
	s_waitcnt lgkmcnt(0)
	v_lshlrev_b32_e32 v65, 16, v104
	v_fma_f32 v108, -v60, v66, v65
	v_and_b32_e32 v65, 0xffff0000, v104
	v_fma_f32 v109, -v61, v66, v65
	v_lshlrev_b32_e32 v65, 16, v103
	v_fma_f32 v102, -v58, v66, v65
	v_and_b32_e32 v65, 0xffff0000, v103
	v_fma_f32 v103, -v59, v66, v65
	v_lshlrev_b32_e32 v65, 16, v105
	v_fma_f32 v104, -v62, v66, v65
	v_and_b32_e32 v65, 0xffff0000, v105
	v_fma_f32 v105, -v63, v66, v65
	v_permlane32_swap_b32_e32 v106, v108
	v_permlane32_swap_b32_e32 v107, v109
	v_pk_mul_f32 v[106:107], v[68:69], v[106:107] op_sel_hi:[0,1]
	v_permlane32_swap_b32_e32 v102, v104
	v_permlane32_swap_b32_e32 v103, v105
	v_pk_mul_f32 v[102:103], v[68:69], v[102:103] op_sel_hi:[0,1]
	v_lshlrev_b32_e32 v110, 16, v90
	v_and_b32_e32 v111, 0xffff0000, v90
	v_mul_f32_e32 v65, 0xbfb8aa3b, v110
	v_exp_f32_e32 v65, v65
	v_mul_f32_e32 v67, 0xbfb8aa3b, v111
	v_exp_f32_e32 v67, v67
	v_pk_mul_f32 v[94:95], v[106:107], v[94:95]
	v_add_f32_e32 v65, 1.0, v65
	v_rcp_f32_e32 v112, v65
	v_add_f32_e32 v65, 1.0, v67
	v_rcp_f32_e32 v113, v65
	v_pk_mul_f32 v[96:97], v[96:97], v[102:103]
	v_lshlrev_b32_e32 v102, 16, v92
	v_and_b32_e32 v103, 0xffff0000, v92
	v_pk_mul_f32 v[106:107], v[112:113], v[110:111]
	v_lshlrev_b32_e32 v110, 16, v91
	v_and_b32_e32 v111, 0xffff0000, v91
	v_mul_f32_e32 v65, 0xbfb8aa3b, v110
	v_exp_f32_e32 v65, v65
	v_mul_f32_e32 v67, 0xbfb8aa3b, v111
	v_exp_f32_e32 v67, v67
	v_pk_mul_f32 v[90:91], v[94:95], v[106:107]
	v_add_f32_e32 v65, 1.0, v65
	v_rcp_f32_e32 v94, v65
	v_add_f32_e32 v65, 1.0, v67
	v_rcp_f32_e32 v95, v65
	v_mul_f32_e32 v65, 0xbfb8aa3b, v102
	v_exp_f32_e32 v65, v65
	v_mul_f32_e32 v67, 0xbfb8aa3b, v103
	v_exp_f32_e32 v67, v67
	v_pk_mul_f32 v[94:95], v[94:95], v[110:111]
	v_cvt_pk_bf16_f32 v90, v90, v91
	v_pk_mul_f32 v[94:95], v[96:97], v[94:95]
	v_add_f32_e32 v65, 1.0, v65
	v_cvt_pk_bf16_f32 v91, v94, v95
	v_pk_mul_f32 v[94:95], v[68:69], v[108:109] op_sel_hi:[0,1]
	v_rcp_f32_e32 v96, v65
	v_add_f32_e32 v65, 1.0, v67
	v_pk_mul_f32 v[94:95], v[94:95], v[98:99]
	v_lshlrev_b32_e32 v98, 16, v93
	v_rcp_f32_e32 v97, v65
	v_and_b32_e32 v99, 0xffff0000, v93
	v_mul_f32_e32 v65, 0xbfb8aa3b, v98
	v_exp_f32_e32 v65, v65
	v_mul_f32_e32 v67, 0xbfb8aa3b, v99
	v_exp_f32_e32 v67, v67
	v_pk_mul_f32 v[96:97], v[96:97], v[102:103]
	v_add_f32_e32 v65, 1.0, v65
	v_pk_mul_f32 v[92:93], v[94:95], v[96:97]
	v_rcp_f32_e32 v94, v65
	v_add_f32_e32 v65, 1.0, v67
	v_rcp_f32_e32 v95, v65
	v_pk_mul_f32 v[96:97], v[68:69], v[104:105] op_sel_hi:[0,1]
	v_pk_mul_f32 v[96:97], v[96:97], v[100:101]
	v_cvt_pk_bf16_f32 v92, v92, v93
	v_pk_mul_f32 v[94:95], v[94:95], v[98:99]
	s_nop 0
	v_pk_mul_f32 v[94:95], v[96:97], v[94:95]
	s_nop 0
	v_cvt_pk_bf16_f32 v93, v94, v95
	global_store_dwordx4 v[186:187], v[90:93], off offset:32
	s_nop 1
	v_mov_b32_e32 v90, v124
	v_mov_b32_e32 v91, v125
	v_mov_b32_e32 v92, v126
	v_mov_b32_e32 v93, v127
	ds_read_b128 v[94:97], v251 offset:128
	ds_read_b128 v[98:101], v251 offset:144
	ds_read2st64_b32 v[102:103], v210 offset0:232 offset1:233
	ds_read2st64_b32 v[104:105], v210 offset0:234 offset1:235
	s_waitcnt lgkmcnt(1)
	v_lshlrev_b32_e32 v65, 16, v102
	v_fma_f32 v106, -v32, v66, v65
	v_and_b32_e32 v65, 0xffff0000, v102
	v_fma_f32 v107, -v33, v66, v65
	s_waitcnt lgkmcnt(0)
	v_lshlrev_b32_e32 v65, 16, v104
	v_fma_f32 v108, -v36, v66, v65
	v_and_b32_e32 v65, 0xffff0000, v104
	v_fma_f32 v109, -v37, v66, v65
	v_lshlrev_b32_e32 v65, 16, v103
	v_fma_f32 v102, -v34, v66, v65
	v_and_b32_e32 v65, 0xffff0000, v103
	v_fma_f32 v103, -v35, v66, v65
	v_lshlrev_b32_e32 v65, 16, v105
	v_fma_f32 v104, -v38, v66, v65
	v_and_b32_e32 v65, 0xffff0000, v105
	v_fma_f32 v105, -v39, v66, v65
	v_permlane32_swap_b32_e32 v106, v108
	v_permlane32_swap_b32_e32 v107, v109
	v_pk_mul_f32 v[106:107], v[68:69], v[106:107] op_sel_hi:[0,1]
	v_permlane32_swap_b32_e32 v102, v104
	v_permlane32_swap_b32_e32 v103, v105
	v_pk_mul_f32 v[102:103], v[68:69], v[102:103] op_sel_hi:[0,1]
	v_lshlrev_b32_e32 v110, 16, v90
	v_and_b32_e32 v111, 0xffff0000, v90
	v_mul_f32_e32 v65, 0xbfb8aa3b, v110
	v_exp_f32_e32 v65, v65
	v_mul_f32_e32 v67, 0xbfb8aa3b, v111
	v_exp_f32_e32 v67, v67
	v_pk_mul_f32 v[94:95], v[106:107], v[94:95]
	v_add_f32_e32 v65, 1.0, v65
	v_rcp_f32_e32 v112, v65
	v_add_f32_e32 v65, 1.0, v67
	v_rcp_f32_e32 v113, v65
	v_pk_mul_f32 v[96:97], v[96:97], v[102:103]
	v_lshlrev_b32_e32 v102, 16, v92
	v_and_b32_e32 v103, 0xffff0000, v92
	v_pk_mul_f32 v[106:107], v[112:113], v[110:111]
	v_lshlrev_b32_e32 v110, 16, v91
	v_and_b32_e32 v111, 0xffff0000, v91
	v_mul_f32_e32 v65, 0xbfb8aa3b, v110
	v_exp_f32_e32 v65, v65
	v_mul_f32_e32 v67, 0xbfb8aa3b, v111
	v_exp_f32_e32 v67, v67
	v_pk_mul_f32 v[90:91], v[94:95], v[106:107]
	v_add_f32_e32 v65, 1.0, v65
	v_rcp_f32_e32 v94, v65
	v_add_f32_e32 v65, 1.0, v67
	v_rcp_f32_e32 v95, v65
	v_mul_f32_e32 v65, 0xbfb8aa3b, v102
	v_exp_f32_e32 v65, v65
	v_mul_f32_e32 v67, 0xbfb8aa3b, v103
	v_exp_f32_e32 v67, v67
	v_pk_mul_f32 v[94:95], v[94:95], v[110:111]
	v_cvt_pk_bf16_f32 v90, v90, v91
	v_pk_mul_f32 v[94:95], v[96:97], v[94:95]
	v_add_f32_e32 v65, 1.0, v65
	v_cvt_pk_bf16_f32 v91, v94, v95
	v_pk_mul_f32 v[94:95], v[68:69], v[108:109] op_sel_hi:[0,1]
	v_rcp_f32_e32 v96, v65
	v_add_f32_e32 v65, 1.0, v67
	v_pk_mul_f32 v[94:95], v[94:95], v[98:99]
	v_lshlrev_b32_e32 v98, 16, v93
	v_rcp_f32_e32 v97, v65
	v_and_b32_e32 v99, 0xffff0000, v93
	v_mul_f32_e32 v65, 0xbfb8aa3b, v98
	v_exp_f32_e32 v65, v65
	v_mul_f32_e32 v67, 0xbfb8aa3b, v99
	v_exp_f32_e32 v67, v67
	v_pk_mul_f32 v[96:97], v[96:97], v[102:103]
	v_add_f32_e32 v65, 1.0, v65
	v_pk_mul_f32 v[92:93], v[94:95], v[96:97]
	v_rcp_f32_e32 v94, v65
	v_add_f32_e32 v65, 1.0, v67
	v_rcp_f32_e32 v95, v65
	v_pk_mul_f32 v[96:97], v[68:69], v[104:105] op_sel_hi:[0,1]
	v_pk_mul_f32 v[96:97], v[96:97], v[100:101]
	v_cvt_pk_bf16_f32 v92, v92, v93
	v_pk_mul_f32 v[94:95], v[94:95], v[98:99]
	s_nop 0
	v_pk_mul_f32 v[94:95], v[96:97], v[94:95]
	s_nop 0
	v_cvt_pk_bf16_f32 v93, v94, v95
	global_store_dwordx4 v[186:187], v[90:93], off offset:64
	s_nop 1
	v_mov_b32_e32 v90, v128
	v_mov_b32_e32 v91, v129
	v_mov_b32_e32 v92, v130
	v_mov_b32_e32 v93, v131
	ds_read_b128 v[94:97], v251 offset:192
	ds_read_b128 v[98:101], v251 offset:208
	ds_read2st64_b32 v[102:103], v210 offset0:236 offset1:237
	ds_read2st64_b32 v[104:105], v210 offset0:238 offset1:239
	s_waitcnt lgkmcnt(1)
	v_lshlrev_b32_e32 v65, 16, v102
	v_fma_f32 v106, -v40, v66, v65
	v_and_b32_e32 v65, 0xffff0000, v102
	v_fma_f32 v107, -v41, v66, v65
	s_waitcnt lgkmcnt(0)
	v_lshlrev_b32_e32 v65, 16, v104
	v_fma_f32 v108, -v44, v66, v65
	v_and_b32_e32 v65, 0xffff0000, v104
	v_fma_f32 v109, -v45, v66, v65
	v_lshlrev_b32_e32 v65, 16, v103
	v_fma_f32 v102, -v42, v66, v65
	v_and_b32_e32 v65, 0xffff0000, v103
	v_fma_f32 v103, -v43, v66, v65
	v_lshlrev_b32_e32 v65, 16, v105
	v_fma_f32 v104, -v46, v66, v65
	v_and_b32_e32 v65, 0xffff0000, v105
	v_fma_f32 v105, -v47, v66, v65
	v_permlane32_swap_b32_e32 v106, v108
	v_permlane32_swap_b32_e32 v107, v109
	v_pk_mul_f32 v[106:107], v[68:69], v[106:107] op_sel_hi:[0,1]
	v_permlane32_swap_b32_e32 v102, v104
	v_permlane32_swap_b32_e32 v103, v105
	v_pk_mul_f32 v[102:103], v[68:69], v[102:103] op_sel_hi:[0,1]
	v_lshlrev_b32_e32 v110, 16, v90
	v_and_b32_e32 v111, 0xffff0000, v90
	v_mul_f32_e32 v65, 0xbfb8aa3b, v110
	v_exp_f32_e32 v65, v65
	v_mul_f32_e32 v67, 0xbfb8aa3b, v111
	v_exp_f32_e32 v67, v67
	v_pk_mul_f32 v[94:95], v[106:107], v[94:95]
	v_add_f32_e32 v65, 1.0, v65
	v_rcp_f32_e32 v112, v65
	v_add_f32_e32 v65, 1.0, v67
	v_rcp_f32_e32 v113, v65
	v_pk_mul_f32 v[96:97], v[96:97], v[102:103]
	v_lshlrev_b32_e32 v102, 16, v92
	v_and_b32_e32 v103, 0xffff0000, v92
	v_pk_mul_f32 v[106:107], v[112:113], v[110:111]
	v_lshlrev_b32_e32 v110, 16, v91
	v_and_b32_e32 v111, 0xffff0000, v91
	v_mul_f32_e32 v65, 0xbfb8aa3b, v110
	v_exp_f32_e32 v65, v65
	v_mul_f32_e32 v67, 0xbfb8aa3b, v111
	v_exp_f32_e32 v67, v67
	v_pk_mul_f32 v[90:91], v[94:95], v[106:107]
	v_add_f32_e32 v65, 1.0, v65
	v_rcp_f32_e32 v94, v65
	v_add_f32_e32 v65, 1.0, v67
	v_rcp_f32_e32 v95, v65
	v_mul_f32_e32 v65, 0xbfb8aa3b, v102
	v_exp_f32_e32 v65, v65
	v_mul_f32_e32 v67, 0xbfb8aa3b, v103
	v_exp_f32_e32 v67, v67
	v_pk_mul_f32 v[94:95], v[94:95], v[110:111]
	v_cvt_pk_bf16_f32 v90, v90, v91
	v_pk_mul_f32 v[94:95], v[96:97], v[94:95]
	v_add_f32_e32 v65, 1.0, v65
	v_cvt_pk_bf16_f32 v91, v94, v95
	v_pk_mul_f32 v[94:95], v[68:69], v[108:109] op_sel_hi:[0,1]
	v_rcp_f32_e32 v96, v65
	v_add_f32_e32 v65, 1.0, v67
	v_pk_mul_f32 v[94:95], v[94:95], v[98:99]
	v_lshlrev_b32_e32 v98, 16, v93
	v_rcp_f32_e32 v97, v65
	v_and_b32_e32 v99, 0xffff0000, v93
	v_mul_f32_e32 v65, 0xbfb8aa3b, v98
	v_exp_f32_e32 v65, v65
	v_mul_f32_e32 v67, 0xbfb8aa3b, v99
	v_exp_f32_e32 v67, v67
	v_pk_mul_f32 v[96:97], v[96:97], v[102:103]
	v_add_f32_e32 v65, 1.0, v65
	v_pk_mul_f32 v[92:93], v[94:95], v[96:97]
	v_rcp_f32_e32 v94, v65
	v_add_f32_e32 v65, 1.0, v67
	v_rcp_f32_e32 v95, v65
	v_pk_mul_f32 v[96:97], v[68:69], v[104:105] op_sel_hi:[0,1]
	v_pk_mul_f32 v[96:97], v[96:97], v[100:101]
	v_cvt_pk_bf16_f32 v92, v92, v93
	v_pk_mul_f32 v[94:95], v[94:95], v[98:99]
	s_nop 0
	v_pk_mul_f32 v[94:95], v[96:97], v[94:95]
	s_nop 0
	v_cvt_pk_bf16_f32 v93, v94, v95
	global_store_dwordx4 v[186:187], v[90:93], off offset:96
	s_nop 1
	v_mov_b32_e32 v90, v132
	v_mov_b32_e32 v91, v133
	v_mov_b32_e32 v92, v134
	v_mov_b32_e32 v93, v135
	ds_read_b128 v[94:97], v251 offset:256
	ds_read_b128 v[98:101], v251 offset:272
	ds_read2st64_b32 v[102:103], v210 offset0:240 offset1:241
	ds_read2st64_b32 v[104:105], v210 offset0:242 offset1:243
	s_waitcnt lgkmcnt(1)
	v_lshlrev_b32_e32 v65, 16, v102
	v_fma_f32 v106, -v16, v66, v65
	v_and_b32_e32 v65, 0xffff0000, v102
	v_fma_f32 v107, -v17, v66, v65
	s_waitcnt lgkmcnt(0)
	v_lshlrev_b32_e32 v65, 16, v104
	v_fma_f32 v108, -v20, v66, v65
	v_and_b32_e32 v65, 0xffff0000, v104
	v_fma_f32 v109, -v21, v66, v65
	v_lshlrev_b32_e32 v65, 16, v103
	v_fma_f32 v102, -v18, v66, v65
	v_and_b32_e32 v65, 0xffff0000, v103
	v_fma_f32 v103, -v19, v66, v65
	v_lshlrev_b32_e32 v65, 16, v105
	v_fma_f32 v104, -v22, v66, v65
	v_and_b32_e32 v65, 0xffff0000, v105
	v_fma_f32 v105, -v23, v66, v65
	v_permlane32_swap_b32_e32 v106, v108
	v_permlane32_swap_b32_e32 v107, v109
	v_pk_mul_f32 v[106:107], v[68:69], v[106:107] op_sel_hi:[0,1]
	v_permlane32_swap_b32_e32 v102, v104
	v_permlane32_swap_b32_e32 v103, v105
	v_pk_mul_f32 v[102:103], v[68:69], v[102:103] op_sel_hi:[0,1]
	v_lshlrev_b32_e32 v110, 16, v90
	v_and_b32_e32 v111, 0xffff0000, v90
	v_mul_f32_e32 v65, 0xbfb8aa3b, v110
	v_exp_f32_e32 v65, v65
	v_mul_f32_e32 v67, 0xbfb8aa3b, v111
	v_exp_f32_e32 v67, v67
	v_pk_mul_f32 v[94:95], v[106:107], v[94:95]
	v_add_f32_e32 v65, 1.0, v65
	v_rcp_f32_e32 v112, v65
	v_add_f32_e32 v65, 1.0, v67
	v_rcp_f32_e32 v113, v65
	v_pk_mul_f32 v[96:97], v[96:97], v[102:103]
	v_lshlrev_b32_e32 v102, 16, v92
	v_and_b32_e32 v103, 0xffff0000, v92
	v_pk_mul_f32 v[106:107], v[112:113], v[110:111]
	v_lshlrev_b32_e32 v110, 16, v91
	v_and_b32_e32 v111, 0xffff0000, v91
	v_mul_f32_e32 v65, 0xbfb8aa3b, v110
	v_exp_f32_e32 v65, v65
	v_mul_f32_e32 v67, 0xbfb8aa3b, v111
	v_exp_f32_e32 v67, v67
	v_pk_mul_f32 v[90:91], v[94:95], v[106:107]
	v_add_f32_e32 v65, 1.0, v65
	v_rcp_f32_e32 v94, v65
	v_add_f32_e32 v65, 1.0, v67
	v_rcp_f32_e32 v95, v65
	v_mul_f32_e32 v65, 0xbfb8aa3b, v102
	v_exp_f32_e32 v65, v65
	v_mul_f32_e32 v67, 0xbfb8aa3b, v103
	v_exp_f32_e32 v67, v67
	v_pk_mul_f32 v[94:95], v[94:95], v[110:111]
	v_cvt_pk_bf16_f32 v90, v90, v91
	v_pk_mul_f32 v[94:95], v[96:97], v[94:95]
	v_add_f32_e32 v65, 1.0, v65
	v_cvt_pk_bf16_f32 v91, v94, v95
	v_pk_mul_f32 v[94:95], v[68:69], v[108:109] op_sel_hi:[0,1]
	v_rcp_f32_e32 v96, v65
	v_add_f32_e32 v65, 1.0, v67
	v_pk_mul_f32 v[94:95], v[94:95], v[98:99]
	v_lshlrev_b32_e32 v98, 16, v93
	v_rcp_f32_e32 v97, v65
	v_and_b32_e32 v99, 0xffff0000, v93
	v_mul_f32_e32 v65, 0xbfb8aa3b, v98
	v_exp_f32_e32 v65, v65
	v_mul_f32_e32 v67, 0xbfb8aa3b, v99
	v_exp_f32_e32 v67, v67
	v_pk_mul_f32 v[96:97], v[96:97], v[102:103]
	v_add_f32_e32 v65, 1.0, v65
	v_pk_mul_f32 v[92:93], v[94:95], v[96:97]
	v_rcp_f32_e32 v94, v65
	v_add_f32_e32 v65, 1.0, v67
	v_rcp_f32_e32 v95, v65
	v_pk_mul_f32 v[96:97], v[68:69], v[104:105] op_sel_hi:[0,1]
	v_pk_mul_f32 v[96:97], v[96:97], v[100:101]
	v_cvt_pk_bf16_f32 v92, v92, v93
	v_pk_mul_f32 v[94:95], v[94:95], v[98:99]
	v_pk_mul_f32 v[86:87], v[86:87], v[66:67] op_sel_hi:[1,0]
	v_pk_mul_f32 v[94:95], v[96:97], v[94:95]
	v_pk_mul_f32 v[88:89], v[88:89], v[66:67] op_sel_hi:[1,0]
	v_cvt_pk_bf16_f32 v93, v94, v95
	global_store_dwordx4 v[186:187], v[90:93], off offset:128
	s_nop 1
	v_mov_b32_e32 v90, v136
	v_mov_b32_e32 v91, v137
	v_mov_b32_e32 v92, v138
	v_mov_b32_e32 v93, v139
	ds_read_b128 v[94:97], v251 offset:320
	ds_read_b128 v[98:101], v251 offset:336
	ds_read2st64_b32 v[102:103], v210 offset0:244 offset1:245
	ds_read2st64_b32 v[104:105], v210 offset0:246 offset1:247
	s_waitcnt lgkmcnt(1)
	v_lshlrev_b32_e32 v65, 16, v102
	v_fma_f32 v106, -v24, v66, v65
	v_and_b32_e32 v65, 0xffff0000, v102
	v_fma_f32 v107, -v25, v66, v65
	s_waitcnt lgkmcnt(0)
	v_lshlrev_b32_e32 v65, 16, v104
	v_sub_f32_e32 v108, v65, v86
	v_and_b32_e32 v65, 0xffff0000, v104
	v_sub_f32_e32 v109, v65, v88
	v_lshlrev_b32_e32 v65, 16, v103
	v_fma_f32 v102, -v26, v66, v65
	v_and_b32_e32 v65, 0xffff0000, v103
	v_fma_f32 v103, -v27, v66, v65
	v_lshlrev_b32_e32 v65, 16, v105
	v_sub_f32_e32 v104, v65, v87
	v_and_b32_e32 v65, 0xffff0000, v105
	v_sub_f32_e32 v105, v65, v89
	v_permlane32_swap_b32_e32 v106, v108
	v_permlane32_swap_b32_e32 v107, v109
	v_pk_mul_f32 v[106:107], v[68:69], v[106:107] op_sel_hi:[0,1]
	v_permlane32_swap_b32_e32 v102, v104
	v_permlane32_swap_b32_e32 v103, v105
	v_lshlrev_b32_e32 v86, 16, v90
	v_and_b32_e32 v87, 0xffff0000, v90
	v_mul_f32_e32 v65, 0xbfb8aa3b, v86
	v_exp_f32_e32 v65, v65
	v_mul_f32_e32 v67, 0xbfb8aa3b, v87
	v_exp_f32_e32 v67, v67
	v_pk_mul_f32 v[94:95], v[106:107], v[94:95]
	v_add_f32_e32 v65, 1.0, v65
	v_rcp_f32_e32 v88, v65
	v_add_f32_e32 v65, 1.0, v67
	v_rcp_f32_e32 v89, v65
	s_nop 0
	v_pk_mul_f32 v[86:87], v[88:89], v[86:87]
	v_lshlrev_b32_e32 v88, 16, v91
	v_and_b32_e32 v89, 0xffff0000, v91
	v_mul_f32_e32 v65, 0xbfb8aa3b, v88
	v_exp_f32_e32 v65, v65
	v_mul_f32_e32 v67, 0xbfb8aa3b, v89
	v_exp_f32_e32 v67, v67
	v_pk_mul_f32 v[86:87], v[94:95], v[86:87]
	v_add_f32_e32 v65, 1.0, v65
	v_rcp_f32_e32 v90, v65
	v_add_f32_e32 v65, 1.0, v67
	v_rcp_f32_e32 v91, v65
	v_pk_mul_f32 v[94:95], v[68:69], v[102:103] op_sel_hi:[0,1]
	v_pk_mul_f32 v[94:95], v[96:97], v[94:95]
	v_cvt_pk_bf16_f32 v86, v86, v87
	v_pk_mul_f32 v[88:89], v[90:91], v[88:89]
	v_lshlrev_b32_e32 v90, 16, v92
	v_and_b32_e32 v91, 0xffff0000, v92
	v_mul_f32_e32 v65, 0xbfb8aa3b, v90
	v_exp_f32_e32 v65, v65
	v_mul_f32_e32 v67, 0xbfb8aa3b, v91
	v_exp_f32_e32 v67, v67
	v_pk_mul_f32 v[88:89], v[94:95], v[88:89]
	v_add_f32_e32 v65, 1.0, v65
	v_rcp_f32_e32 v94, v65
	v_add_f32_e32 v65, 1.0, v67
	v_lshlrev_b32_e32 v92, 16, v93
	v_rcp_f32_e32 v95, v65
	v_and_b32_e32 v93, 0xffff0000, v93
	v_mul_f32_e32 v65, 0xbfb8aa3b, v92
	v_exp_f32_e32 v65, v65
	v_mul_f32_e32 v67, 0xbfb8aa3b, v93
	v_exp_f32_e32 v67, v67
	v_cvt_pk_bf16_f32 v87, v88, v89
	v_pk_mul_f32 v[88:89], v[68:69], v[108:109] op_sel_hi:[0,1]
	v_pk_mul_f32 v[88:89], v[88:89], v[98:99]
	v_pk_mul_f32 v[90:91], v[94:95], v[90:91]
	v_add_f32_e32 v65, 1.0, v65
	v_pk_mul_f32 v[88:89], v[88:89], v[90:91]
	v_rcp_f32_e32 v90, v65
	v_add_f32_e32 v65, 1.0, v67
	v_rcp_f32_e32 v91, v65
	v_pk_mul_f32 v[94:95], v[68:69], v[104:105] op_sel_hi:[0,1]
	v_pk_mul_f32 v[94:95], v[94:95], v[100:101]
	v_cvt_pk_bf16_f32 v88, v88, v89
	v_pk_mul_f32 v[90:91], v[90:91], v[92:93]
	v_pk_mul_f32 v[78:79], v[78:79], v[66:67] op_sel_hi:[1,0]
	v_pk_mul_f32 v[90:91], v[94:95], v[90:91]
	v_pk_mul_f32 v[80:81], v[80:81], v[66:67] op_sel_hi:[1,0]
	v_cvt_pk_bf16_f32 v89, v90, v91
	global_store_dwordx4 v[186:187], v[86:89], off offset:160
	s_nop 1
	v_mov_b32_e32 v86, v140
	v_mov_b32_e32 v87, v141
	v_mov_b32_e32 v88, v142
	v_mov_b32_e32 v89, v143
	ds_read_b128 v[90:93], v251 offset:384
	ds_read_b128 v[94:97], v251 offset:400
	ds_read2st64_b32 v[98:99], v210 offset0:248 offset1:249
	ds_read2st64_b32 v[100:101], v210 offset0:250 offset1:251
	v_pk_mul_f32 v[82:83], v[82:83], v[66:67] op_sel_hi:[1,0]
	v_pk_mul_f32 v[84:85], v[84:85], v[66:67] op_sel_hi:[1,0]
	s_waitcnt lgkmcnt(1)
	v_lshlrev_b32_e32 v65, 16, v98
	v_sub_f32_e32 v102, v65, v78
	v_and_b32_e32 v65, 0xffff0000, v98
	v_sub_f32_e32 v103, v65, v80
	s_waitcnt lgkmcnt(0)
	v_lshlrev_b32_e32 v65, 16, v100
	v_sub_f32_e32 v104, v65, v82
	v_and_b32_e32 v65, 0xffff0000, v100
	v_sub_f32_e32 v105, v65, v84
	v_lshlrev_b32_e32 v65, 16, v99
	v_sub_f32_e32 v80, v65, v79
	v_and_b32_e32 v65, 0xffff0000, v99
	v_sub_f32_e32 v81, v65, v81
	v_lshlrev_b32_e32 v65, 16, v101
	v_sub_f32_e32 v82, v65, v83
	v_and_b32_e32 v65, 0xffff0000, v101
	v_sub_f32_e32 v83, v65, v85
	v_permlane32_swap_b32_e32 v80, v82
	s_nop 0
	v_permlane32_swap_b32_e32 v81, v83
	v_pk_mul_f32 v[80:81], v[68:69], v[80:81] op_sel_hi:[0,1]
	v_permlane32_swap_b32_e32 v102, v104
	v_permlane32_swap_b32_e32 v103, v105
	v_pk_mul_f32 v[98:99], v[68:69], v[102:103] op_sel_hi:[0,1]
	v_pk_mul_f32 v[82:83], v[68:69], v[82:83] op_sel_hi:[0,1]
	v_lshlrev_b32_e32 v78, 16, v86
	v_and_b32_e32 v79, 0xffff0000, v86
	v_mul_f32_e32 v65, 0xbfb8aa3b, v78
	v_exp_f32_e32 v65, v65
	v_mul_f32_e32 v67, 0xbfb8aa3b, v79
	v_exp_f32_e32 v67, v67
	v_pk_mul_f32 v[80:81], v[92:93], v[80:81]
	v_add_f32_e32 v65, 1.0, v65
	v_rcp_f32_e32 v84, v65
	v_add_f32_e32 v65, 1.0, v67
	v_rcp_f32_e32 v85, v65
	v_pk_mul_f32 v[90:91], v[98:99], v[90:91]
	v_pk_mul_f32 v[82:83], v[82:83], v[96:97]
	v_pk_mul_f32 v[78:79], v[84:85], v[78:79]
	v_lshlrev_b32_e32 v84, 16, v87
	v_and_b32_e32 v85, 0xffff0000, v87
	v_mul_f32_e32 v65, 0xbfb8aa3b, v84
	v_exp_f32_e32 v65, v65
	v_mul_f32_e32 v67, 0xbfb8aa3b, v85
	v_exp_f32_e32 v67, v67
	v_pk_mul_f32 v[78:79], v[90:91], v[78:79]
	v_add_f32_e32 v65, 1.0, v65
	v_rcp_f32_e32 v86, v65
	v_add_f32_e32 v65, 1.0, v67
	v_rcp_f32_e32 v87, v65
	v_cvt_pk_bf16_f32 v78, v78, v79
	v_pk_mul_f32 v[84:85], v[86:87], v[84:85]
	v_lshlrev_b32_e32 v86, 16, v88
	v_and_b32_e32 v87, 0xffff0000, v88
	v_mul_f32_e32 v65, 0xbfb8aa3b, v86
	v_exp_f32_e32 v65, v65
	v_mul_f32_e32 v67, 0xbfb8aa3b, v87
	v_exp_f32_e32 v67, v67
	v_pk_mul_f32 v[80:81], v[80:81], v[84:85]
	v_add_f32_e32 v65, 1.0, v65
	v_rcp_f32_e32 v84, v65
	v_add_f32_e32 v65, 1.0, v67
	v_rcp_f32_e32 v85, v65
	v_cvt_pk_bf16_f32 v79, v80, v81
	v_pk_mul_f32 v[80:81], v[68:69], v[104:105] op_sel_hi:[0,1]
	v_pk_mul_f32 v[80:81], v[80:81], v[94:95]
	v_pk_mul_f32 v[84:85], v[84:85], v[86:87]
	v_lshlrev_b32_e32 v86, 16, v89
	v_and_b32_e32 v87, 0xffff0000, v89
	v_mul_f32_e32 v65, 0xbfb8aa3b, v86
	v_exp_f32_e32 v65, v65
	v_mul_f32_e32 v67, 0xbfb8aa3b, v87
	v_exp_f32_e32 v67, v67
	v_pk_mul_f32 v[80:81], v[80:81], v[84:85]
	v_add_f32_e32 v65, 1.0, v65
	v_rcp_f32_e32 v84, v65
	v_add_f32_e32 v65, 1.0, v67
	v_rcp_f32_e32 v85, v65
	v_cvt_pk_bf16_f32 v80, v80, v81
	v_pk_mul_f32 v[70:71], v[70:71], v[66:67] op_sel_hi:[1,0]
	v_pk_mul_f32 v[72:73], v[72:73], v[66:67] op_sel_hi:[1,0]
	v_pk_mul_f32 v[84:85], v[84:85], v[86:87]
	v_pk_mul_f32 v[74:75], v[74:75], v[66:67] op_sel_hi:[1,0]
	v_pk_mul_f32 v[82:83], v[82:83], v[84:85]
	v_pk_mul_f32 v[66:67], v[76:77], v[66:67] op_sel_hi:[1,0]
	v_cvt_pk_bf16_f32 v81, v82, v83
	global_store_dwordx4 v[186:187], v[78:81], off offset:192
	s_nop 1
	v_mov_b32_e32 v78, v144
	v_mov_b32_e32 v79, v145
	v_mov_b32_e32 v80, v146
	v_mov_b32_e32 v81, v147
	ds_read_b128 v[82:85], v251 offset:448
	ds_read_b128 v[86:89], v251 offset:464
	ds_read2st64_b32 v[90:91], v210 offset0:252 offset1:253
	ds_read2st64_b32 v[76:77], v210 offset0:254 offset1:255
	s_waitcnt lgkmcnt(1)
	v_lshlrev_b32_e32 v65, 16, v90
	v_sub_f32_e32 v92, v65, v70
	v_and_b32_e32 v65, 0xffff0000, v90
	v_sub_f32_e32 v93, v65, v72
	s_waitcnt lgkmcnt(0)
	v_lshlrev_b32_e32 v65, 16, v76
	v_sub_f32_e32 v94, v65, v74
	v_and_b32_e32 v65, 0xffff0000, v76
	v_sub_f32_e32 v95, v65, v66
	v_lshlrev_b32_e32 v65, 16, v91
	v_sub_f32_e32 v72, v65, v71
	v_and_b32_e32 v65, 0xffff0000, v91
	v_sub_f32_e32 v73, v65, v73
	v_lshlrev_b32_e32 v65, 16, v77
	v_sub_f32_e32 v66, v65, v75
	v_and_b32_e32 v65, 0xffff0000, v77
	v_sub_f32_e32 v67, v65, v67
	v_permlane32_swap_b32_e32 v92, v94
	v_permlane32_swap_b32_e32 v93, v95
	v_permlane32_swap_b32_e32 v72, v66
	v_permlane32_swap_b32_e32 v73, v67
	v_lshlrev_b32_e32 v70, 16, v78
	v_and_b32_e32 v71, 0xffff0000, v78
	v_mul_f32_e32 v65, 0xbfb8aa3b, v70
	v_exp_f32_e32 v65, v65
	v_mul_f32_e32 v69, 0xbfb8aa3b, v71
	v_exp_f32_e32 v69, v69
	v_add_f32_e32 v65, 1.0, v65
	v_rcp_f32_e32 v74, v65
	v_add_f32_e32 v65, 1.0, v69
	v_rcp_f32_e32 v75, v65
	v_pk_mul_f32 v[76:77], v[68:69], v[92:93] op_sel_hi:[0,1]
	v_pk_mul_f32 v[76:77], v[76:77], v[82:83]
	v_pk_mul_f32 v[70:71], v[74:75], v[70:71]
	v_lshlrev_b32_e32 v74, 16, v79
	v_and_b32_e32 v75, 0xffff0000, v79
	v_mul_f32_e32 v65, 0xbfb8aa3b, v74
	v_exp_f32_e32 v65, v65
	v_mul_f32_e32 v69, 0xbfb8aa3b, v75
	v_exp_f32_e32 v69, v69
	v_pk_mul_f32 v[70:71], v[76:77], v[70:71]
	v_add_f32_e32 v65, 1.0, v65
	v_rcp_f32_e32 v76, v65
	v_add_f32_e32 v65, 1.0, v69
	v_rcp_f32_e32 v77, v65
	v_pk_mul_f32 v[72:73], v[68:69], v[72:73] op_sel_hi:[0,1]
	v_pk_mul_f32 v[72:73], v[84:85], v[72:73]
	v_cvt_pk_bf16_f32 v70, v70, v71
	v_pk_mul_f32 v[74:75], v[76:77], v[74:75]
	v_lshlrev_b32_e32 v76, 16, v80
	v_and_b32_e32 v77, 0xffff0000, v80
	v_mul_f32_e32 v65, 0xbfb8aa3b, v76
	v_exp_f32_e32 v65, v65
	v_mul_f32_e32 v69, 0xbfb8aa3b, v77
	v_exp_f32_e32 v69, v69
	v_pk_mul_f32 v[72:73], v[72:73], v[74:75]
	v_add_f32_e32 v65, 1.0, v65
	v_rcp_f32_e32 v74, v65
	v_add_f32_e32 v65, 1.0, v69
	v_rcp_f32_e32 v75, v65
	v_cvt_pk_bf16_f32 v71, v72, v73
	v_pk_mul_f32 v[72:73], v[68:69], v[94:95] op_sel_hi:[0,1]
	v_pk_mul_f32 v[72:73], v[72:73], v[86:87]
	v_pk_mul_f32 v[74:75], v[74:75], v[76:77]
	v_lshlrev_b32_e32 v76, 16, v81
	v_and_b32_e32 v77, 0xffff0000, v81
	v_mul_f32_e32 v65, 0xbfb8aa3b, v76
	v_exp_f32_e32 v65, v65
	v_mul_f32_e32 v69, 0xbfb8aa3b, v77
	v_exp_f32_e32 v69, v69
	v_pk_mul_f32 v[72:73], v[72:73], v[74:75]
	v_add_f32_e32 v65, 1.0, v65
	v_rcp_f32_e32 v74, v65
	v_add_f32_e32 v65, 1.0, v69
	v_rcp_f32_e32 v75, v65
	v_pk_mul_f32 v[66:67], v[68:69], v[66:67] op_sel_hi:[0,1]
	v_pk_mul_f32 v[66:67], v[66:67], v[88:89]
	v_cvt_pk_bf16_f32 v72, v72, v73
	v_pk_mul_f32 v[68:69], v[74:75], v[76:77]
	s_nop 0
	v_pk_mul_f32 v[66:67], v[66:67], v[68:69]
	s_nop 0
	v_cvt_pk_bf16_f32 v73, v66, v67
	global_store_dwordx4 v[186:187], v[70:73], off offset:224
	s_cbranch_execnz .LBB0_420
	s_branch .LBB0_435
